# stick-breaking attention: early-exit flags read with two 16-byte LDS reads instead of eight dependent 4-byte reads; running-sum bookkeeping as one subtraction chain
# speedup vs baseline: 1.0009x; 1.0000x over previous
.Lstk_nm1:
	v_exp_f32_e64 v200, -|v82|
	v_exp_f32_e64 v201, -|v83|
	v_exp_f32_e64 v202, -|v84|
	v_exp_f32_e64 v203, -|v85|
	v_pk_add_f32 v[200:201], v[200:201], v[236:237] op_sel_hi:[1,0]
	v_max_i32_e32 v174, 0, v82
	v_max_i32_e32 v175, 0, v83
	v_log_f32_e32 v200, v200
	v_log_f32_e32 v201, v201
	v_exp_f32_e64 v204, -|v86|
	v_exp_f32_e64 v205, -|v87|
	v_pk_add_f32 v[202:203], v[202:203], v[236:237] op_sel_hi:[1,0]
	v_max_i32_e32 v176, 0, v84
	v_max_i32_e32 v177, 0, v85
	v_log_f32_e32 v202, v202
	v_log_f32_e32 v203, v203
	v_pk_add_f32 v[200:201], v[200:201], v[174:175]
	v_pk_add_f32 v[82:83], v[82:83], v[200:201] neg_lo:[0,1] neg_hi:[0,1]
	v_exp_f32_e64 v206, -|v88|
	v_exp_f32_e64 v207, -|v89|
	v_pk_add_f32 v[204:205], v[204:205], v[236:237] op_sel_hi:[1,0]
	v_max_i32_e32 v174, 0, v86
	v_max_i32_e32 v175, 0, v87
	v_log_f32_e32 v204, v204
	v_log_f32_e32 v205, v205
	v_pk_add_f32 v[202:203], v[202:203], v[176:177]
	v_pk_add_f32 v[84:85], v[84:85], v[202:203] neg_lo:[0,1] neg_hi:[0,1]
	v_exp_f32_e64 v208, -|v90|
	v_exp_f32_e64 v209, -|v91|
	v_pk_add_f32 v[206:207], v[206:207], v[236:237] op_sel_hi:[1,0]
	v_max_i32_e32 v176, 0, v88
	v_max_i32_e32 v177, 0, v89
	v_log_f32_e32 v206, v206
	v_log_f32_e32 v207, v207
	v_pk_add_f32 v[204:205], v[204:205], v[174:175]
	v_pk_add_f32 v[86:87], v[86:87], v[204:205] neg_lo:[0,1] neg_hi:[0,1]
	v_exp_f32_e64 v210, -|v92|
	v_exp_f32_e64 v211, -|v93|
	v_pk_add_f32 v[208:209], v[208:209], v[236:237] op_sel_hi:[1,0]
	v_max_i32_e32 v174, 0, v90
	v_max_i32_e32 v175, 0, v91
	v_log_f32_e32 v208, v208
	v_log_f32_e32 v209, v209
	v_pk_add_f32 v[206:207], v[206:207], v[176:177]
	v_pk_add_f32 v[88:89], v[88:89], v[206:207] neg_lo:[0,1] neg_hi:[0,1]
	v_exp_f32_e64 v212, -|v94|
	v_exp_f32_e64 v213, -|v95|
	v_pk_add_f32 v[210:211], v[210:211], v[236:237] op_sel_hi:[1,0]
	v_max_i32_e32 v176, 0, v92
	v_max_i32_e32 v177, 0, v93
	v_log_f32_e32 v210, v210
	v_log_f32_e32 v211, v211
	v_pk_add_f32 v[208:209], v[208:209], v[174:175]
	v_pk_add_f32 v[90:91], v[90:91], v[208:209] neg_lo:[0,1] neg_hi:[0,1]
	v_exp_f32_e64 v214, -|v96|
	v_exp_f32_e64 v215, -|v97|
	v_pk_add_f32 v[212:213], v[212:213], v[236:237] op_sel_hi:[1,0]
	v_max_i32_e32 v174, 0, v94
	v_max_i32_e32 v175, 0, v95
	v_log_f32_e32 v212, v212
	v_log_f32_e32 v213, v213
	v_pk_add_f32 v[210:211], v[210:211], v[176:177]
	v_pk_add_f32 v[92:93], v[92:93], v[210:211] neg_lo:[0,1] neg_hi:[0,1]
	v_pk_add_f32 v[214:215], v[214:215], v[236:237] op_sel_hi:[1,0]
	v_max_i32_e32 v176, 0, v96
	v_max_i32_e32 v177, 0, v97
	v_log_f32_e32 v214, v214
	v_log_f32_e32 v215, v215
	v_pk_add_f32 v[212:213], v[212:213], v[174:175]
	v_pk_add_f32 v[94:95], v[94:95], v[212:213] neg_lo:[0,1] neg_hi:[0,1]
	v_pk_add_f32 v[214:215], v[214:215], v[176:177]
	v_pk_add_f32 v[96:97], v[96:97], v[214:215] neg_lo:[0,1] neg_hi:[0,1]
	v_pk_add_f32 v[174:175], v[200:201], v[202:203]
	v_add_f32_e32 v216, v174, v175
	v_mov_b32_e32 v220, v216
	v_pk_add_f32 v[176:177], v[204:205], v[206:207]
	v_add_f32_e32 v217, v176, v177
	v_mov_b32_e32 v221, v217
	v_pk_add_f32 v[174:175], v[208:209], v[210:211]
	v_add_f32_e32 v218, v174, v175
	v_mov_b32_e32 v222, v218
	v_pk_add_f32 v[176:177], v[212:213], v[214:215]
	v_add_f32_e32 v219, v176, v177
	v_mov_b32_e32 v223, v219
	s_nop 1
	v_permlane32_swap_b32_e32 v216, v220
	v_permlane32_swap_b32_e32 v217, v221
	v_permlane32_swap_b32_e32 v218, v222
	v_permlane32_swap_b32_e32 v219, v223
	v_add_f32_e32 v216, v216, v220
	v_add_f32_e32 v217, v217, v221
	v_add_f32_e32 v218, v218, v222
	v_add_f32_e32 v219, v219, v223
	v_fma_f32 v233, -v223, v173, v172
	v_sub_f32_e32 v232, v233, v215
	v_sub_f32_e32 v229, v232, v214
	v_sub_f32_e32 v228, v229, v213
	v_pk_add_f32 v[96:97], v[96:97], v[232:233]
	v_pk_add_f32 v[94:95], v[94:95], v[228:229]
	v_exp_f32_e32 v96, v96
	v_exp_f32_e32 v97, v97
	v_exp_f32_e32 v94, v94
	v_exp_f32_e32 v95, v95
	v_sub_f32_e32 v227, v172, v219
	v_fma_f32 v177, -v222, v173, v227
	v_sub_f32_e32 v176, v177, v211
	v_sub_f32_e32 v235, v176, v210
	v_sub_f32_e32 v234, v235, v209
	v_pk_add_f32 v[92:93], v[92:93], v[176:177]
	v_pk_add_f32 v[90:91], v[90:91], v[234:235]
	v_exp_f32_e32 v92, v92
	v_exp_f32_e32 v93, v93
	v_exp_f32_e32 v90, v90
	v_exp_f32_e32 v91, v91
	v_sub_f32_e32 v226, v227, v218
	v_fma_f32 v233, -v221, v173, v226
	v_sub_f32_e32 v232, v233, v207
	v_sub_f32_e32 v229, v232, v206
	v_sub_f32_e32 v228, v229, v205
	v_pk_add_f32 v[88:89], v[88:89], v[232:233]
	v_pk_add_f32 v[86:87], v[86:87], v[228:229]
	v_exp_f32_e32 v88, v88
	v_exp_f32_e32 v89, v89
	v_exp_f32_e32 v86, v86
	v_exp_f32_e32 v87, v87
	v_sub_f32_e32 v227, v226, v217
	v_fma_f32 v177, -v220, v173, v227
	v_sub_f32_e32 v182, v227, v216
	v_sub_f32_e32 v176, v177, v203
	v_sub_f32_e32 v235, v176, v202
	v_sub_f32_e32 v234, v235, v201
	v_pk_add_f32 v[84:85], v[84:85], v[176:177]
	v_pk_add_f32 v[82:83], v[82:83], v[234:235]
	v_exp_f32_e32 v84, v84
	v_exp_f32_e32 v85, v85
	v_exp_f32_e32 v82, v82
	v_exp_f32_e32 v83, v83
	v_add_u32_e32 v199, 32, v159
	v_cmp_gt_i32_e32 vcc, 28, v199
	s_cmp_eq_u64 vcc, 0
	s_cbranch_scc1 .Lstk_nm0
	v_cmp_lt_i32_e64 s[0:1], 0, v199
	v_cmp_lt_i32_e64 s[8:9], 1, v199
	v_cmp_lt_i32_e64 s[10:11], 2, v199
	v_cmp_lt_i32_e64 s[12:13], 3, v199
	v_cndmask_b32_e64 v66, v231, v66, s[0:1]
	v_cndmask_b32_e64 v67, v231, v67, s[8:9]
	v_cndmask_b32_e64 v68, v231, v68, s[10:11]
	v_cndmask_b32_e64 v69, v231, v69, s[12:13]
	v_cmp_lt_i32_e64 s[0:1], 8, v199
	v_cmp_lt_i32_e64 s[8:9], 9, v199
	v_cmp_lt_i32_e64 s[10:11], 10, v199
	v_cmp_lt_i32_e64 s[12:13], 11, v199
	v_cndmask_b32_e64 v70, v231, v70, s[0:1]
	v_cndmask_b32_e64 v71, v231, v71, s[8:9]
	v_cndmask_b32_e64 v72, v231, v72, s[10:11]
	v_cndmask_b32_e64 v73, v231, v73, s[12:13]
	v_cmp_lt_i32_e64 s[0:1], 16, v199
	v_cmp_lt_i32_e64 s[8:9], 17, v199
	v_cmp_lt_i32_e64 s[10:11], 18, v199
	v_cmp_lt_i32_e64 s[12:13], 19, v199
	v_cndmask_b32_e64 v74, v231, v74, s[0:1]
	v_cndmask_b32_e64 v75, v231, v75, s[8:9]
	v_cndmask_b32_e64 v76, v231, v76, s[10:11]
	v_cndmask_b32_e64 v77, v231, v77, s[12:13]
	v_cmp_lt_i32_e64 s[0:1], 24, v199
	v_cmp_lt_i32_e64 s[8:9], 25, v199
	v_cmp_lt_i32_e64 s[10:11], 26, v199
	v_cmp_lt_i32_e64 s[12:13], 27, v199
	v_cndmask_b32_e64 v78, v231, v78, s[0:1]
	v_cndmask_b32_e64 v79, v231, v79, s[8:9]
	v_cndmask_b32_e64 v80, v231, v80, s[10:11]
	v_cndmask_b32_e64 v81, v231, v81, s[12:13]
.Lstk_nm0:
	v_exp_f32_e64 v200, -|v66|
	v_exp_f32_e64 v201, -|v67|
	v_exp_f32_e64 v202, -|v68|
	v_exp_f32_e64 v203, -|v69|
	v_pk_add_f32 v[200:201], v[200:201], v[236:237] op_sel_hi:[1,0]
	v_max_i32_e32 v174, 0, v66
	v_max_i32_e32 v175, 0, v67
	v_log_f32_e32 v200, v200
	v_log_f32_e32 v201, v201
	v_exp_f32_e64 v204, -|v70|
	v_exp_f32_e64 v205, -|v71|
	v_pk_add_f32 v[202:203], v[202:203], v[236:237] op_sel_hi:[1,0]
	v_max_i32_e32 v176, 0, v68
	v_max_i32_e32 v177, 0, v69
	v_log_f32_e32 v202, v202
	v_log_f32_e32 v203, v203
	v_pk_add_f32 v[200:201], v[200:201], v[174:175]
	v_pk_add_f32 v[66:67], v[66:67], v[200:201] neg_lo:[0,1] neg_hi:[0,1]
	v_exp_f32_e64 v206, -|v72|
	v_exp_f32_e64 v207, -|v73|
	v_pk_add_f32 v[204:205], v[204:205], v[236:237] op_sel_hi:[1,0]
	v_max_i32_e32 v174, 0, v70
	v_max_i32_e32 v175, 0, v71
	v_log_f32_e32 v204, v204
	v_log_f32_e32 v205, v205
	v_pk_add_f32 v[202:203], v[202:203], v[176:177]
	v_pk_add_f32 v[68:69], v[68:69], v[202:203] neg_lo:[0,1] neg_hi:[0,1]
	v_exp_f32_e64 v208, -|v74|
	v_exp_f32_e64 v209, -|v75|
	v_pk_add_f32 v[206:207], v[206:207], v[236:237] op_sel_hi:[1,0]
	v_max_i32_e32 v176, 0, v72
	v_max_i32_e32 v177, 0, v73
	v_log_f32_e32 v206, v206
	v_log_f32_e32 v207, v207
	v_pk_add_f32 v[204:205], v[204:205], v[174:175]
	v_pk_add_f32 v[70:71], v[70:71], v[204:205] neg_lo:[0,1] neg_hi:[0,1]
	v_exp_f32_e64 v210, -|v76|
	v_exp_f32_e64 v211, -|v77|
	v_pk_add_f32 v[208:209], v[208:209], v[236:237] op_sel_hi:[1,0]
	v_max_i32_e32 v174, 0, v74
	v_max_i32_e32 v175, 0, v75
	v_log_f32_e32 v208, v208
	v_log_f32_e32 v209, v209
	v_pk_add_f32 v[206:207], v[206:207], v[176:177]
	v_pk_add_f32 v[72:73], v[72:73], v[206:207] neg_lo:[0,1] neg_hi:[0,1]
	v_exp_f32_e64 v212, -|v78|
	v_exp_f32_e64 v213, -|v79|
	v_pk_add_f32 v[210:211], v[210:211], v[236:237] op_sel_hi:[1,0]
	v_max_i32_e32 v176, 0, v76
	v_max_i32_e32 v177, 0, v77
	v_log_f32_e32 v210, v210
	v_log_f32_e32 v211, v211
	v_pk_add_f32 v[208:209], v[208:209], v[174:175]
	v_pk_add_f32 v[74:75], v[74:75], v[208:209] neg_lo:[0,1] neg_hi:[0,1]
	v_exp_f32_e64 v214, -|v80|
	v_exp_f32_e64 v215, -|v81|
	v_pk_add_f32 v[212:213], v[212:213], v[236:237] op_sel_hi:[1,0]
	v_max_i32_e32 v174, 0, v78
	v_max_i32_e32 v175, 0, v79
	v_log_f32_e32 v212, v212
	v_log_f32_e32 v213, v213
	v_pk_add_f32 v[210:211], v[210:211], v[176:177]
	v_pk_add_f32 v[76:77], v[76:77], v[210:211] neg_lo:[0,1] neg_hi:[0,1]
	v_pk_add_f32 v[214:215], v[214:215], v[236:237] op_sel_hi:[1,0]
	v_max_i32_e32 v176, 0, v80
	v_max_i32_e32 v177, 0, v81
	v_log_f32_e32 v214, v214
	v_log_f32_e32 v215, v215
	v_pk_add_f32 v[212:213], v[212:213], v[174:175]
	v_pk_add_f32 v[78:79], v[78:79], v[212:213] neg_lo:[0,1] neg_hi:[0,1]
	v_pk_add_f32 v[214:215], v[214:215], v[176:177]
	v_pk_add_f32 v[80:81], v[80:81], v[214:215] neg_lo:[0,1] neg_hi:[0,1]
	v_pk_add_f32 v[174:175], v[200:201], v[202:203]
	v_add_f32_e32 v216, v174, v175
	v_mov_b32_e32 v220, v216
	v_pk_add_f32 v[176:177], v[204:205], v[206:207]
	v_add_f32_e32 v217, v176, v177
	v_mov_b32_e32 v221, v217
	v_pk_add_f32 v[174:175], v[208:209], v[210:211]
	v_add_f32_e32 v218, v174, v175
	v_mov_b32_e32 v222, v218
	v_pk_add_f32 v[176:177], v[212:213], v[214:215]
	v_add_f32_e32 v219, v176, v177
	v_mov_b32_e32 v223, v219
	s_nop 1
	v_permlane32_swap_b32_e32 v216, v220
	v_permlane32_swap_b32_e32 v217, v221
	v_permlane32_swap_b32_e32 v218, v222
	v_permlane32_swap_b32_e32 v219, v223
	v_add_f32_e32 v216, v216, v220
	v_add_f32_e32 v217, v217, v221
	v_add_f32_e32 v218, v218, v222
	v_add_f32_e32 v219, v219, v223
	v_fma_f32 v233, -v223, v173, v182
	v_sub_f32_e32 v232, v233, v215
	v_sub_f32_e32 v229, v232, v214
	v_sub_f32_e32 v228, v229, v213
	v_pk_add_f32 v[80:81], v[80:81], v[232:233]
	v_pk_add_f32 v[78:79], v[78:79], v[228:229]
	v_exp_f32_e32 v80, v80
	v_exp_f32_e32 v81, v81
	v_exp_f32_e32 v78, v78
	v_exp_f32_e32 v79, v79
	v_sub_f32_e32 v227, v182, v219
	v_fma_f32 v177, -v222, v173, v227
	v_sub_f32_e32 v176, v177, v211
	v_sub_f32_e32 v235, v176, v210
	v_sub_f32_e32 v234, v235, v209
	v_pk_add_f32 v[76:77], v[76:77], v[176:177]
	v_pk_add_f32 v[74:75], v[74:75], v[234:235]
	v_exp_f32_e32 v76, v76
	v_exp_f32_e32 v77, v77
	v_exp_f32_e32 v74, v74
	v_exp_f32_e32 v75, v75
	v_sub_f32_e32 v226, v227, v218
	v_fma_f32 v233, -v221, v173, v226
	v_sub_f32_e32 v232, v233, v207
	v_sub_f32_e32 v229, v232, v206
	v_sub_f32_e32 v228, v229, v205
	v_pk_add_f32 v[72:73], v[72:73], v[232:233]
	v_pk_add_f32 v[70:71], v[70:71], v[228:229]
	v_exp_f32_e32 v72, v72
	v_exp_f32_e32 v73, v73
	v_exp_f32_e32 v70, v70
	v_exp_f32_e32 v71, v71
	v_sub_f32_e32 v227, v226, v217
	v_fma_f32 v177, -v220, v173, v227
	v_sub_f32_e32 v230, v227, v216
	v_sub_f32_e32 v176, v177, v203
	v_sub_f32_e32 v235, v176, v202
	v_sub_f32_e32 v234, v235, v201
	v_pk_add_f32 v[68:69], v[68:69], v[176:177]
	v_pk_add_f32 v[66:67], v[66:67], v[234:235]
	v_exp_f32_e32 v68, v68
	v_exp_f32_e32 v69, v69
	v_exp_f32_e32 v66, v66
	v_exp_f32_e32 v67, v67
	v_sub_f32_e32 v173, v230, v172
	v_add_u32_e32 v0, v0, v191
	v_cvt_pk_bf16_f32 v66, v66, v67
	v_cvt_pk_bf16_f32 v67, v68, v69
	v_cvt_pk_bf16_f32 v68, v70, v71
	v_cvt_pk_bf16_f32 v69, v72, v73
	v_cvt_pk_bf16_f32 v70, v74, v75
	v_cvt_pk_bf16_f32 v71, v76, v77
	v_cvt_pk_bf16_f32 v72, v78, v79
	v_cvt_pk_bf16_f32 v73, v80, v81
	v_cvt_pk_bf16_f32 v74, v82, v83
	v_cvt_pk_bf16_f32 v75, v84, v85
	v_cvt_pk_bf16_f32 v76, v86, v87
	v_cvt_pk_bf16_f32 v77, v88, v89
	v_cvt_pk_bf16_f32 v78, v90, v91
	v_cvt_pk_bf16_f32 v79, v92, v93
	v_cvt_pk_bf16_f32 v80, v94, v95
	v_cvt_pk_bf16_f32 v81, v96, v97
	ds_read_b128 v[82:85], v0 offset:17408
	ds_read_b128 v[86:89], v0 offset:22016
	ds_read_b128 v[90:93], v0 offset:26624
	ds_read_b128 v[94:97], v0 offset:31232
	s_setprio 1
	s_waitcnt lgkmcnt(3)
	v_mfma_f32_32x32x16_bf16 v[50:65], v[82:85], v[66:69], v[50:65]
	s_waitcnt lgkmcnt(2)
	v_mfma_f32_32x32x16_bf16 v[34:49], v[86:89], v[66:69], v[34:49]
	s_waitcnt lgkmcnt(1)
	v_mfma_f32_32x32x16_bf16 v[18:33], v[90:93], v[66:69], v[18:33]
	s_waitcnt lgkmcnt(0)
	v_mfma_f32_32x32x16_bf16 v[2:17], v[94:97], v[66:69], v[2:17]
	s_setprio 0
	ds_read_b128 v[66:69], v0 offset:17440
	ds_read_b128 v[82:85], v0 offset:22048
	ds_read_b128 v[86:89], v0 offset:26656
	ds_read_b128 v[90:93], v0 offset:31264
	s_setprio 1
	s_waitcnt lgkmcnt(3)
	v_mfma_f32_32x32x16_bf16 v[50:65], v[66:69], v[70:73], v[50:65]
	s_waitcnt lgkmcnt(2)
	v_mfma_f32_32x32x16_bf16 v[34:49], v[82:85], v[70:73], v[34:49]
	s_waitcnt lgkmcnt(1)
	v_mfma_f32_32x32x16_bf16 v[18:33], v[86:89], v[70:73], v[18:33]
	s_waitcnt lgkmcnt(0)
	v_mfma_f32_32x32x16_bf16 v[2:17], v[90:93], v[70:73], v[2:17]
	s_setprio 0
	ds_read_b128 v[66:69], v0 offset:17472
	ds_read_b128 v[70:73], v0 offset:22080
	ds_read_b128 v[82:85], v0 offset:26688
	ds_read_b128 v[86:89], v0 offset:31296
	s_setprio 1
	s_waitcnt lgkmcnt(3)
	v_mfma_f32_32x32x16_bf16 v[50:65], v[66:69], v[74:77], v[50:65]
	s_waitcnt lgkmcnt(2)
	v_mfma_f32_32x32x16_bf16 v[34:49], v[70:73], v[74:77], v[34:49]
	s_waitcnt lgkmcnt(1)
	v_mfma_f32_32x32x16_bf16 v[18:33], v[82:85], v[74:77], v[18:33]
	s_waitcnt lgkmcnt(0)
	v_mfma_f32_32x32x16_bf16 v[2:17], v[86:89], v[74:77], v[2:17]
	s_setprio 0
	ds_read_b128 v[66:69], v0 offset:17504
	ds_read_b128 v[70:73], v0 offset:22112
	ds_read_b128 v[74:77], v0 offset:26720
	ds_read_b128 v[82:85], v0 offset:31328
	s_setprio 1
	s_waitcnt lgkmcnt(3)
	v_mfma_f32_32x32x16_bf16 v[50:65], v[66:69], v[78:81], v[50:65]
	s_waitcnt lgkmcnt(2)
	v_mfma_f32_32x32x16_bf16 v[34:49], v[70:73], v[78:81], v[34:49]
	s_waitcnt lgkmcnt(1)
	v_mfma_f32_32x32x16_bf16 v[18:33], v[74:77], v[78:81], v[18:33]
	s_waitcnt lgkmcnt(0)
	v_mfma_f32_32x32x16_bf16 v[2:17], v[82:85], v[78:81], v[2:17]
	s_setprio 0
	v_add_f32_e32 v172, v172, v173

.LBB0_46:
	s_mov_b64 s[8:9], exec
	v_cmp_gt_f32_e32 vcc, s58, v172
	s_lshl_b32 s10, s45, 5
	s_and_saveexec_b64 s[0:1], s[6:7]
	s_cmp_eq_u64 vcc, s[8:9]
	s_cselect_b64 s[8:9], -1, 0
	v_add_u32_e32 v0, s10, v190
	v_cndmask_b32_e64 v66, 0, 1, s[8:9]
	ds_write_b32 v0, v66
	s_or_b64 exec, exec, s[0:1]
	s_add_i32 s0, s10, 0
	s_add_i32 s0, s0, 0x11800
	v_mov_b32_e32 v0, s0
	s_waitcnt lgkmcnt(0)
	s_barrier
	ds_read_b128 v[66:69], v0
	ds_read_b128 v[70:73], v0 offset:16
	s_movk_i32 s8, 0xff80
	s_mov_b32 s9, -1
	v_add_u32_e32 v159, 64, v159
	v_lshl_add_u64 v[170:171], v[170:171], 0, s[8:9]
	v_lshl_add_u64 v[166:167], v[166:167], 0, s[60:61]
	v_lshl_add_u64 v[168:169], v[168:169], 0, s[60:61]
	v_subrev_u32_e32 v198, 64, v198
	s_add_i32 s42, s42, 1
	s_waitcnt lgkmcnt(0)
	v_and_b32_e32 v66, v66, v67
	v_and_b32_e32 v68, v68, v69
	v_and_b32_e32 v70, v70, v71
	v_and_b32_e32 v72, v72, v73
	v_and_b32_e32 v66, v66, v68
	v_and_b32_e32 v70, v70, v72
	v_and_b32_e32 v0, v66, v70
	v_cmp_ne_u32_e64 s[0:1], 0, v0
	s_and_b64 vcc, exec, s[0:1]
	s_cbranch_vccz .LBB0_38
	s_branch .LBB0_35
